# GEMM K-loops: dead issue slots removed (mid-segment setprio flip pair, repeated lgkmcnt wait) with the loop heads pinned to 64-byte boundaries
# speedup vs baseline: 1.0109x; 1.0070x over previous
.LBB0_874:
	s_add_i32 s63, s18, 0xf80
	ds_read_b128 v[146:149], v141
	ds_read_b128 v[150:153], v141 offset:1024
	ds_read_b128 v[154:157], v141 offset:2048
	ds_read_b128 v[158:161], v141 offset:3072
	ds_read_b128 v[162:165], v140
	ds_read_b128 v[166:169], v140 offset:1024
	ds_read_b128 v[170:173], v140 offset:2048
	ds_read_b128 v[174:177], v140 offset:3072
	s_and_b32 s63, s63, 0xf80
	s_add_u32 s63, s16, s63
	s_addc_u32 s65, s17, 0
	s_add_u32 s64, s63, 0x80000
	s_mov_b32 m0, s51
	s_addc_u32 s65, s65, 0
	ds_read_b128 v[178:181], v137
	ds_read_b128 v[182:185], v137 offset:1024
	ds_read_b128 v[186:189], v137 offset:2048
	ds_read_b128 v[190:193], v137 offset:3072
	ds_read_b128 v[194:197], v137 offset:4096
	ds_read_b128 v[198:201], v137 offset:5120
	ds_read_b128 v[202:205], v137 offset:6144
	ds_read_b128 v[206:209], v137 offset:7168
	global_load_lds_dwordx4 v130, s[64:65]
	s_mov_b32 m0, s50
	v_mov_b32_e32 v129, v131
	global_load_lds_dwordx4 v128, s[64:65]
	s_waitcnt vmcnt(8)
	s_waitcnt lgkmcnt(0)
	s_barrier
	s_setprio 1
	v_mfma_f32_16x16x32_bf16 v[124:127], v[146:149], v[178:181], v[124:127]
	v_mfma_f32_16x16x32_bf16 v[120:123], v[154:157], v[178:181], v[120:123]
	v_mfma_f32_16x16x32_bf16 v[116:119], v[146:149], v[186:189], v[116:119]
	v_mfma_f32_16x16x32_bf16 v[112:115], v[154:157], v[186:189], v[112:115]
	v_mfma_f32_16x16x32_bf16 v[108:111], v[146:149], v[194:197], v[108:111]
	v_mfma_f32_16x16x32_bf16 v[104:107], v[154:157], v[194:197], v[104:107]
	v_mfma_f32_16x16x32_bf16 v[100:103], v[146:149], v[202:205], v[100:103]
	v_mfma_f32_16x16x32_bf16 v[96:99], v[154:157], v[202:205], v[96:99]
	v_mfma_f32_16x16x32_bf16 v[124:127], v[150:153], v[182:185], v[124:127]
	v_mfma_f32_16x16x32_bf16 v[120:123], v[158:161], v[182:185], v[120:123]
	v_mfma_f32_16x16x32_bf16 v[116:119], v[150:153], v[190:193], v[116:119]
	v_mfma_f32_16x16x32_bf16 v[112:115], v[158:161], v[190:193], v[112:115]
	v_mfma_f32_16x16x32_bf16 v[108:111], v[150:153], v[198:201], v[108:111]
	v_mfma_f32_16x16x32_bf16 v[104:107], v[158:161], v[198:201], v[104:107]
	v_mfma_f32_16x16x32_bf16 v[100:103], v[150:153], v[206:209], v[100:103]
	v_mfma_f32_16x16x32_bf16 v[96:99], v[158:161], v[206:209], v[96:99]
	v_mfma_f32_16x16x32_bf16 v[92:95], v[162:165], v[178:181], v[92:95]
	v_mfma_f32_16x16x32_bf16 v[88:91], v[170:173], v[178:181], v[88:91]
	v_mfma_f32_16x16x32_bf16 v[84:87], v[162:165], v[186:189], v[84:87]
	v_mfma_f32_16x16x32_bf16 v[80:83], v[170:173], v[186:189], v[80:83]
	v_mfma_f32_16x16x32_bf16 v[76:79], v[162:165], v[194:197], v[76:79]
	v_mfma_f32_16x16x32_bf16 v[72:75], v[170:173], v[194:197], v[72:75]
	v_mfma_f32_16x16x32_bf16 v[68:71], v[162:165], v[202:205], v[68:71]
	v_mfma_f32_16x16x32_bf16 v[64:67], v[170:173], v[202:205], v[64:67]
	v_mfma_f32_16x16x32_bf16 v[92:95], v[166:169], v[182:185], v[92:95]
	v_mfma_f32_16x16x32_bf16 v[88:91], v[174:177], v[182:185], v[88:91]
	v_mfma_f32_16x16x32_bf16 v[84:87], v[166:169], v[190:193], v[84:87]
	v_mfma_f32_16x16x32_bf16 v[80:83], v[174:177], v[190:193], v[80:83]
	v_mfma_f32_16x16x32_bf16 v[76:79], v[166:169], v[198:201], v[76:79]
	v_mfma_f32_16x16x32_bf16 v[72:75], v[174:177], v[198:201], v[72:75]
	v_mfma_f32_16x16x32_bf16 v[68:71], v[166:169], v[206:209], v[68:71]
	v_mfma_f32_16x16x32_bf16 v[64:67], v[174:177], v[206:209], v[64:67]
	s_setprio 0
	s_barrier
	s_add_u32 s64, s38, s18
	v_mov_b32_e32 v133, v131
	s_addc_u32 s65, s39, s19
	v_lshl_add_u64 v[210:211], s[64:65], 0, v[132:133]
	s_mov_b32 m0, s49
	v_lshl_add_u64 v[212:213], v[210:211], 0, s[20:21]
	v_mov_b32_e32 v135, v131
	ds_read_b128 v[178:181], v137 offset:16384
	ds_read_b128 v[182:185], v137 offset:17408
	ds_read_b128 v[186:189], v137 offset:18432
	ds_read_b128 v[190:193], v137 offset:19456
	ds_read_b128 v[194:197], v137 offset:20480
	ds_read_b128 v[198:201], v137 offset:21504
	ds_read_b128 v[202:205], v137 offset:22528
	ds_read_b128 v[206:209], v137 offset:23552
	global_load_lds_dwordx4 v[212:213], off
	v_lshl_add_u64 v[212:213], s[64:65], 0, v[134:135]
	v_lshl_add_u64 v[214:215], v[212:213], 0, s[20:21]
	s_mov_b32 m0, s47
	s_add_u32 s64, s53, s18
	global_load_lds_dwordx4 v[214:215], off
	v_lshl_add_u64 v[214:215], v[210:211], 0, s[22:23]
	s_mov_b32 m0, s48
	s_addc_u32 s65, s61, s19
	global_load_lds_dwordx4 v[214:215], off
	v_lshl_add_u64 v[214:215], v[212:213], 0, s[22:23]
	s_mov_b32 m0, s46
	s_nop 0
	global_load_lds_dwordx4 v[214:215], off
	v_lshl_add_u64 v[214:215], s[64:65], 0, v[130:131]
	v_lshl_add_u64 v[216:217], v[214:215], 0, s[24:25]
	s_mov_b32 m0, s40
	s_nop 0
	global_load_lds_dwordx4 v[216:217], off
	v_lshl_add_u64 v[216:217], s[64:65], 0, v[128:129]
	v_lshl_add_u64 v[218:219], v[216:217], 0, s[24:25]
	s_mov_b32 m0, s45
	s_nop 0
	global_load_lds_dwordx4 v[218:219], off
	s_waitcnt vmcnt(8)
	s_waitcnt lgkmcnt(0)
	s_barrier
	s_setprio 1
	v_mfma_f32_16x16x32_bf16 v[60:63], v[146:149], v[178:181], v[60:63]
	v_mfma_f32_16x16x32_bf16 v[56:59], v[154:157], v[178:181], v[56:59]
	v_mfma_f32_16x16x32_bf16 v[52:55], v[146:149], v[186:189], v[52:55]
	v_mfma_f32_16x16x32_bf16 v[48:51], v[154:157], v[186:189], v[48:51]
	v_mfma_f32_16x16x32_bf16 v[44:47], v[146:149], v[194:197], v[44:47]
	v_mfma_f32_16x16x32_bf16 v[40:43], v[154:157], v[194:197], v[40:43]
	v_mfma_f32_16x16x32_bf16 v[36:39], v[146:149], v[202:205], v[36:39]
	v_mfma_f32_16x16x32_bf16 v[32:35], v[154:157], v[202:205], v[32:35]
	v_mfma_f32_16x16x32_bf16 v[60:63], v[150:153], v[182:185], v[60:63]
	v_mfma_f32_16x16x32_bf16 v[56:59], v[158:161], v[182:185], v[56:59]
	v_mfma_f32_16x16x32_bf16 v[52:55], v[150:153], v[190:193], v[52:55]
	v_mfma_f32_16x16x32_bf16 v[48:51], v[158:161], v[190:193], v[48:51]
	v_mfma_f32_16x16x32_bf16 v[44:47], v[150:153], v[198:201], v[44:47]
	v_mfma_f32_16x16x32_bf16 v[40:43], v[158:161], v[198:201], v[40:43]
	v_mfma_f32_16x16x32_bf16 v[36:39], v[150:153], v[206:209], v[36:39]
	v_mfma_f32_16x16x32_bf16 v[32:35], v[158:161], v[206:209], v[32:35]
	v_mfma_f32_16x16x32_bf16 v[28:31], v[162:165], v[178:181], v[28:31]
	v_mfma_f32_16x16x32_bf16 v[24:27], v[170:173], v[178:181], v[24:27]
	v_mfma_f32_16x16x32_bf16 v[20:23], v[162:165], v[186:189], v[20:23]
	v_mfma_f32_16x16x32_bf16 v[16:19], v[170:173], v[186:189], v[16:19]
	v_mfma_f32_16x16x32_bf16 v[12:15], v[162:165], v[194:197], v[12:15]
	v_mfma_f32_16x16x32_bf16 v[8:11], v[170:173], v[194:197], v[8:11]
	v_mfma_f32_16x16x32_bf16 v[4:7], v[162:165], v[202:205], v[4:7]
	v_mfma_f32_16x16x32_bf16 v[0:3], v[170:173], v[202:205], v[0:3]
	v_mfma_f32_16x16x32_bf16 v[28:31], v[166:169], v[182:185], v[28:31]
	v_mfma_f32_16x16x32_bf16 v[24:27], v[174:177], v[182:185], v[24:27]
	v_mfma_f32_16x16x32_bf16 v[20:23], v[166:169], v[190:193], v[20:23]
	v_mfma_f32_16x16x32_bf16 v[16:19], v[174:177], v[190:193], v[16:19]
	v_mfma_f32_16x16x32_bf16 v[12:15], v[166:169], v[198:201], v[12:15]
	v_mfma_f32_16x16x32_bf16 v[8:11], v[174:177], v[198:201], v[8:11]
	v_mfma_f32_16x16x32_bf16 v[4:7], v[166:169], v[206:209], v[4:7]
	v_mfma_f32_16x16x32_bf16 v[0:3], v[174:177], v[206:209], v[0:3]
	s_setprio 0
	s_barrier
	ds_read_b128 v[146:149], v139
	ds_read_b128 v[150:153], v139 offset:1024
	ds_read_b128 v[154:157], v139 offset:2048
	ds_read_b128 v[158:161], v139 offset:3072
	ds_read_b128 v[162:165], v138
	ds_read_b128 v[166:169], v138 offset:1024
	ds_read_b128 v[170:173], v138 offset:2048
	ds_read_b128 v[174:177], v138 offset:3072
	s_mov_b32 m0, s34
	v_lshl_add_u64 v[218:219], v[214:215], 0, s[26:27]
	ds_read_b128 v[178:181], v137 offset:32768
	ds_read_b128 v[182:185], v137 offset:33792
	ds_read_b128 v[186:189], v137 offset:34816
	ds_read_b128 v[190:193], v137 offset:35840
	ds_read_b128 v[194:197], v137 offset:36864
	ds_read_b128 v[198:201], v137 offset:37888
	ds_read_b128 v[202:205], v137 offset:38912
	ds_read_b128 v[206:209], v137 offset:39936
	global_load_lds_dwordx4 v[218:219], off
	v_lshl_add_u64 v[218:219], v[216:217], 0, s[26:27]
	s_mov_b32 m0, s35
	s_nop 0
	global_load_lds_dwordx4 v[218:219], off
	s_waitcnt vmcnt(8)
	s_waitcnt lgkmcnt(0)
	s_barrier
	s_setprio 1
	v_mfma_f32_16x16x32_bf16 v[124:127], v[146:149], v[178:181], v[124:127]
	v_mfma_f32_16x16x32_bf16 v[120:123], v[154:157], v[178:181], v[120:123]
	v_mfma_f32_16x16x32_bf16 v[116:119], v[146:149], v[186:189], v[116:119]
	v_mfma_f32_16x16x32_bf16 v[112:115], v[154:157], v[186:189], v[112:115]
	v_mfma_f32_16x16x32_bf16 v[108:111], v[146:149], v[194:197], v[108:111]
	v_mfma_f32_16x16x32_bf16 v[104:107], v[154:157], v[194:197], v[104:107]
	v_mfma_f32_16x16x32_bf16 v[100:103], v[146:149], v[202:205], v[100:103]
	v_mfma_f32_16x16x32_bf16 v[96:99], v[154:157], v[202:205], v[96:99]
	v_mfma_f32_16x16x32_bf16 v[124:127], v[150:153], v[182:185], v[124:127]
	v_mfma_f32_16x16x32_bf16 v[120:123], v[158:161], v[182:185], v[120:123]
	v_mfma_f32_16x16x32_bf16 v[116:119], v[150:153], v[190:193], v[116:119]
	v_mfma_f32_16x16x32_bf16 v[112:115], v[158:161], v[190:193], v[112:115]
	v_mfma_f32_16x16x32_bf16 v[108:111], v[150:153], v[198:201], v[108:111]
	v_mfma_f32_16x16x32_bf16 v[104:107], v[158:161], v[198:201], v[104:107]
	v_mfma_f32_16x16x32_bf16 v[100:103], v[150:153], v[206:209], v[100:103]
	v_mfma_f32_16x16x32_bf16 v[96:99], v[158:161], v[206:209], v[96:99]
	v_mfma_f32_16x16x32_bf16 v[92:95], v[162:165], v[178:181], v[92:95]
	v_mfma_f32_16x16x32_bf16 v[88:91], v[170:173], v[178:181], v[88:91]
	v_mfma_f32_16x16x32_bf16 v[84:87], v[162:165], v[186:189], v[84:87]
	v_mfma_f32_16x16x32_bf16 v[80:83], v[170:173], v[186:189], v[80:83]
	v_mfma_f32_16x16x32_bf16 v[76:79], v[162:165], v[194:197], v[76:79]
	v_mfma_f32_16x16x32_bf16 v[72:75], v[170:173], v[194:197], v[72:75]
	v_mfma_f32_16x16x32_bf16 v[68:71], v[162:165], v[202:205], v[68:71]
	v_mfma_f32_16x16x32_bf16 v[64:67], v[170:173], v[202:205], v[64:67]
	v_mfma_f32_16x16x32_bf16 v[92:95], v[166:169], v[182:185], v[92:95]
	v_mfma_f32_16x16x32_bf16 v[88:91], v[174:177], v[182:185], v[88:91]
	v_mfma_f32_16x16x32_bf16 v[84:87], v[166:169], v[190:193], v[84:87]
	v_mfma_f32_16x16x32_bf16 v[80:83], v[174:177], v[190:193], v[80:83]
	v_mfma_f32_16x16x32_bf16 v[76:79], v[166:169], v[198:201], v[76:79]
	v_mfma_f32_16x16x32_bf16 v[72:75], v[174:177], v[198:201], v[72:75]
	v_mfma_f32_16x16x32_bf16 v[68:71], v[166:169], v[206:209], v[68:71]
	v_mfma_f32_16x16x32_bf16 v[64:67], v[174:177], v[206:209], v[64:67]
	s_setprio 0
	s_barrier
; template <int ROT, class Epi0, class Epi1, class Late, class Post0>
; __device__ __forceinline__ void gemm_phase_pair(PG8_LAS unsigned char* lds, const Gemm g0, const Gemm g1, const Unit u, const Epi0& E0, const Epi1& E1, int wid_in, const Late& late, const Post0& post0) {
;     ...
;     const int t_late = ROT != 0 ? nt0 - ROT - 2 : 0;
;     for (int t = 0; t < t_late; t += 2) {
;         const char* a1 = cA + PG8_KT(t + 1); const char* a2 = cA + PG8_KT(t + 2); const char* b2 = cB + PG8_KT(t + 2); const char* a3 = cA + PG8_KT(t + 3); const char* b3 = cB + PG8_KT(t + 3);
;         PG8_PAIR_ITER(a1 + hs0, vA0, a2, b2, a3, b3, vA0, vB0, hs0);
	s_mov_b32 m0, s44
	v_lshl_add_u64 v[218:219], v[210:211], 0, s[28:29]
	ds_read_b128 v[178:181], v137 offset:49152
	ds_read_b128 v[182:185], v137 offset:50176
	ds_read_b128 v[186:189], v137 offset:51200
	ds_read_b128 v[190:193], v137 offset:52224
	ds_read_b128 v[194:197], v137 offset:53248
	ds_read_b128 v[198:201], v137 offset:54272
	ds_read_b128 v[202:205], v137 offset:55296
	ds_read_b128 v[206:209], v137 offset:56320
	global_load_lds_dwordx4 v[218:219], off
	v_lshl_add_u64 v[218:219], v[212:213], 0, s[28:29]
	s_mov_b32 m0, s42
	v_lshl_add_u64 v[210:211], v[210:211], 0, s[30:31]
	global_load_lds_dwordx4 v[218:219], off
	s_mov_b32 m0, s43
	s_nop 0
	global_load_lds_dwordx4 v[210:211], off
	v_lshl_add_u64 v[210:211], v[212:213], 0, s[30:31]
	s_mov_b32 m0, s41
	s_nop 0
	global_load_lds_dwordx4 v[210:211], off
	v_lshl_add_u64 v[210:211], v[214:215], 0, s[36:37]
	s_mov_b32 m0, s13
	s_nop 0
	global_load_lds_dwordx4 v[210:211], off
	v_lshl_add_u64 v[210:211], v[216:217], 0, s[36:37]
	s_mov_b32 m0, s33
	s_nop 0
	global_load_lds_dwordx4 v[210:211], off
	s_waitcnt vmcnt(8)
	s_waitcnt lgkmcnt(0)
	s_barrier
	s_setprio 1
	v_mfma_f32_16x16x32_bf16 v[60:63], v[146:149], v[178:181], v[60:63]
	v_mfma_f32_16x16x32_bf16 v[56:59], v[154:157], v[178:181], v[56:59]
	v_mfma_f32_16x16x32_bf16 v[52:55], v[146:149], v[186:189], v[52:55]
	v_mfma_f32_16x16x32_bf16 v[48:51], v[154:157], v[186:189], v[48:51]
	v_mfma_f32_16x16x32_bf16 v[44:47], v[146:149], v[194:197], v[44:47]
	v_mfma_f32_16x16x32_bf16 v[40:43], v[154:157], v[194:197], v[40:43]
	v_mfma_f32_16x16x32_bf16 v[36:39], v[146:149], v[202:205], v[36:39]
	v_mfma_f32_16x16x32_bf16 v[32:35], v[154:157], v[202:205], v[32:35]
	v_mfma_f32_16x16x32_bf16 v[60:63], v[150:153], v[182:185], v[60:63]
	v_mfma_f32_16x16x32_bf16 v[56:59], v[158:161], v[182:185], v[56:59]
	v_mfma_f32_16x16x32_bf16 v[52:55], v[150:153], v[190:193], v[52:55]
	v_mfma_f32_16x16x32_bf16 v[48:51], v[158:161], v[190:193], v[48:51]
	v_mfma_f32_16x16x32_bf16 v[44:47], v[150:153], v[198:201], v[44:47]
	v_mfma_f32_16x16x32_bf16 v[40:43], v[158:161], v[198:201], v[40:43]
	v_mfma_f32_16x16x32_bf16 v[36:39], v[150:153], v[206:209], v[36:39]
	v_mfma_f32_16x16x32_bf16 v[32:35], v[158:161], v[206:209], v[32:35]
	v_mfma_f32_16x16x32_bf16 v[28:31], v[162:165], v[178:181], v[28:31]
	v_mfma_f32_16x16x32_bf16 v[24:27], v[170:173], v[178:181], v[24:27]
	v_mfma_f32_16x16x32_bf16 v[20:23], v[162:165], v[186:189], v[20:23]
	v_mfma_f32_16x16x32_bf16 v[16:19], v[170:173], v[186:189], v[16:19]
	v_mfma_f32_16x16x32_bf16 v[12:15], v[162:165], v[194:197], v[12:15]
	v_mfma_f32_16x16x32_bf16 v[8:11], v[170:173], v[194:197], v[8:11]
	v_mfma_f32_16x16x32_bf16 v[4:7], v[162:165], v[202:205], v[4:7]
	v_mfma_f32_16x16x32_bf16 v[0:3], v[170:173], v[202:205], v[0:3]
	v_mfma_f32_16x16x32_bf16 v[28:31], v[166:169], v[182:185], v[28:31]
	v_mfma_f32_16x16x32_bf16 v[24:27], v[174:177], v[182:185], v[24:27]
	v_mfma_f32_16x16x32_bf16 v[20:23], v[166:169], v[190:193], v[20:23]
	v_mfma_f32_16x16x32_bf16 v[16:19], v[174:177], v[190:193], v[16:19]
	v_mfma_f32_16x16x32_bf16 v[12:15], v[166:169], v[198:201], v[12:15]
	v_mfma_f32_16x16x32_bf16 v[8:11], v[174:177], v[198:201], v[8:11]
	v_mfma_f32_16x16x32_bf16 v[4:7], v[166:169], v[206:209], v[4:7]
	v_mfma_f32_16x16x32_bf16 v[0:3], v[174:177], v[206:209], v[0:3]
	s_setprio 0
	s_barrier
	s_add_i32 s62, s62, 2
	s_add_u32 s18, s18, 0x100
	s_addc_u32 s19, s19, 0
	s_cmp_gt_u32 s62, 27
	s_cbranch_scc1 .LBB0_877
	.p2align	6
